# FF1 hidden-activation output stores with the non-temporal hint (streaming output; keeps the GEMM operand tiles in L2)
# baseline (speedup 1.0000x reference)
.LBB0_32:
	s_cmp_lg_u32 s32, 0
	s_cbranch_scc1 .Lff1_cached
	v_lshlrev_b32_e32 v232, 2, v177
	v_add_u32_e32 v232, 0x20000, v232
	v_lshl_add_u32 v174, s4, 8, v177
	v_readlane_b32 s0, v249, 32
	v_or_b32_e32 v172, 16, v174
	v_ashrrev_i32_e32 v175, 31, v174
	v_readlane_b32 s1, v249, 33
	v_ashrrev_i32_e32 v173, 31, v172
	v_or_b32_e32 v170, 32, v174
	v_or_b32_e32 v168, 48, v174
	v_lshl_add_u64 v[130:131], v[174:175], 4, s[0:1]
	v_lshl_add_u64 v[132:133], v[172:173], 4, s[0:1]
	v_ashrrev_i32_e32 v171, 31, v170
	v_ashrrev_i32_e32 v169, 31, v168
	v_add_u32_e32 v166, 0x80, v174
	v_add_u32_e32 v164, 0x90, v174
	global_load_dwordx4 v[184:187], v[130:131], off
	global_load_dwordx4 v[188:191], v[132:133], off
	v_lshl_add_u64 v[130:131], v[170:171], 4, s[0:1]
	v_lshl_add_u64 v[132:133], v[168:169], 4, s[0:1]
	v_ashrrev_i32_e32 v167, 31, v166
	v_ashrrev_i32_e32 v165, 31, v164
	v_add_u32_e32 v162, 0xa0, v174
	v_add_u32_e32 v160, 0xb0, v174
	global_load_dwordx4 v[192:195], v[130:131], off
	global_load_dwordx4 v[146:149], v[132:133], off
	v_lshl_add_u64 v[130:131], v[166:167], 4, s[0:1]
	v_lshl_add_u64 v[132:133], v[164:165], 4, s[0:1]
	v_ashrrev_i32_e32 v163, 31, v162
	v_ashrrev_i32_e32 v161, 31, v160
	global_load_dwordx4 v[142:145], v[130:131], off
	global_load_dwordx4 v[138:141], v[132:133], off
	v_lshl_add_u64 v[130:131], v[162:163], 4, s[0:1]
	v_lshl_add_u64 v[132:133], v[160:161], 4, s[0:1]
	global_load_dwordx4 v[134:137], v[130:131], off
	s_nop 0
	global_load_dwordx4 v[130:133], v[132:133], off
	s_waitcnt vmcnt(0)
	v_mov_b32_e32 v196, v185
	v_mov_b32_e32 v197, v186
	v_mov_b32_e32 v185, v187
	v_pk_add_f32 v[184:185], v[196:197], v[184:185]
	s_mov_b32 s4, 0xf800000
	v_add_f32_e32 v176, v184, v185
	v_fmamk_f32 v176, v176, 0x3a800000, v234
	v_cmp_gt_f32_e32 vcc, s4, v176
	v_mul_f32_e32 v178, 0x4f800000, v176
	s_nop 0
	v_cndmask_b32_e32 v176, v176, v178, vcc
	v_sqrt_f32_e32 v178, v176
	s_nop 0
	v_add_u32_e32 v180, -1, v178
	v_fma_f32 v183, -v180, v178, v176
	v_cmp_ge_f32_e64 s[0:1], 0, v183
	v_add_u32_e32 v183, 1, v178
	s_nop 0
	v_cndmask_b32_e64 v180, v178, v180, s[0:1]
	v_fma_f32 v178, -v183, v178, v176
	v_cmp_lt_f32_e64 s[0:1], 0, v178
	s_nop 1
	v_cndmask_b32_e64 v178, v180, v183, s[0:1]
	v_mul_f32_e32 v180, 0x37800000, v178
	v_cndmask_b32_e32 v178, v178, v180, vcc
	v_cmp_class_f32_e32 vcc, v176, v235
	s_nop 1
	v_cndmask_b32_e32 v176, v178, v176, vcc
	v_div_scale_f32 v178, s[0:1], v176, v176, 1.0
	v_rcp_f32_e32 v180, v178
	s_nop 0
	v_fma_f32 v183, -v178, v180, 1.0
	v_fmac_f32_e32 v180, v183, v180
	v_div_scale_f32 v183, vcc, 1.0, v176, 1.0
	v_mul_f32_e32 v184, v183, v180
	v_fma_f32 v185, -v178, v184, v183
	v_fmac_f32_e32 v184, v185, v180
	v_fma_f32 v178, -v178, v184, v183
	v_div_fmas_f32 v178, v178, v180, v184
	v_mov_b32_e32 v184, v189
	v_mov_b32_e32 v185, v190
	v_mov_b32_e32 v189, v191
	v_pk_add_f32 v[184:185], v[184:185], v[188:189]
	v_div_fixup_f32 v176, v178, v176, 1.0
	ds_write_b32 v232, v176 offset:0
	v_add_f32_e32 v178, v184, v185
	v_fmamk_f32 v178, v178, 0x3a800000, v234
	v_cmp_gt_f32_e32 vcc, s4, v178
	v_mul_f32_e32 v180, 0x4f800000, v178
	v_pk_mul_f32 v[122:123], v[122:123], v[176:177] op_sel_hi:[1,0]
	v_cndmask_b32_e32 v178, v178, v180, vcc
	v_sqrt_f32_e32 v180, v178
	v_pk_mul_f32 v[126:127], v[126:127], v[176:177] op_sel_hi:[1,0]
	v_pk_mul_f32 v[124:125], v[124:125], v[176:177] op_sel_hi:[1,0]
	v_max_f32_e32 v122, 0, v122
	v_add_u32_e32 v183, -1, v180
	v_fma_f32 v184, -v183, v180, v178
	v_cmp_ge_f32_e64 s[0:1], 0, v184
	v_add_u32_e32 v184, 1, v180
	v_pk_mul_f32 v[128:129], v[128:129], v[176:177] op_sel_hi:[1,0]
	v_cndmask_b32_e64 v183, v180, v183, s[0:1]
	v_fma_f32 v180, -v184, v180, v178
	v_cmp_lt_f32_e64 s[0:1], 0, v180
	v_max_f32_e32 v123, 0, v123
	v_max_f32_e32 v124, 0, v124
	v_cndmask_b32_e64 v180, v183, v184, s[0:1]
	v_mul_f32_e32 v183, 0x37800000, v180
	v_cndmask_b32_e32 v180, v180, v183, vcc
	v_cmp_class_f32_e32 vcc, v178, v235
	v_max_f32_e32 v126, 0, v126
	v_max_f32_e32 v125, 0, v125
	v_cndmask_b32_e32 v178, v180, v178, vcc
	v_div_scale_f32 v180, s[0:1], v178, v178, 1.0
	v_rcp_f32_e32 v183, v180
	v_pk_mul_f32 v[116:117], v[116:117], v[176:177] op_sel_hi:[1,0]
	v_pk_mul_f32 v[114:115], v[114:115], v[176:177] op_sel_hi:[1,0]
	v_mul_f32_e32 v126, v126, v126
	v_fma_f32 v184, -v180, v183, 1.0
	v_fmac_f32_e32 v183, v184, v183
	v_div_scale_f32 v184, vcc, 1.0, v178, 1.0
	v_mul_f32_e32 v185, v184, v183
	v_fma_f32 v186, -v180, v185, v184
	v_fmac_f32_e32 v185, v186, v183
	v_fma_f32 v180, -v180, v185, v184
	v_div_fmas_f32 v180, v180, v183, v185
	v_mov_b32_e32 v184, v193
	v_mov_b32_e32 v185, v194
	v_mov_b32_e32 v193, v195
	v_pk_add_f32 v[184:185], v[184:185], v[192:193]
	v_div_fixup_f32 v178, v180, v178, 1.0
	ds_write_b32 v232, v178 offset:64
	v_add_f32_e32 v180, v184, v185
	v_fmamk_f32 v180, v180, 0x3a800000, v234
	v_cmp_gt_f32_e32 vcc, s4, v180
	v_mul_f32_e32 v183, 0x4f800000, v180
	v_mul_f32_e32 v125, v125, v125
	v_cndmask_b32_e32 v180, v180, v183, vcc
	v_sqrt_f32_e32 v183, v180
	v_pk_mul_f32 v[120:121], v[120:121], v[176:177] op_sel_hi:[1,0]
	v_pk_mul_f32 v[118:119], v[118:119], v[176:177] op_sel_hi:[1,0]
	v_max_f32_e32 v114, 0, v114
	v_add_u32_e32 v184, -1, v183
	v_fma_f32 v185, -v184, v183, v180
	v_cmp_ge_f32_e64 s[0:1], 0, v185
	v_add_u32_e32 v185, 1, v183
	v_max_f32_e32 v115, 0, v115
	v_cndmask_b32_e64 v184, v183, v184, s[0:1]
	v_fma_f32 v183, -v185, v183, v180
	v_cmp_lt_f32_e64 s[0:1], 0, v183
	v_max_f32_e32 v116, 0, v116
	v_max_f32_e32 v118, 0, v118
	v_cndmask_b32_e64 v183, v184, v185, s[0:1]
	v_mul_f32_e32 v184, 0x37800000, v183
	v_cndmask_b32_e32 v183, v183, v184, vcc
	v_cmp_class_f32_e32 vcc, v180, v235
	v_max_f32_e32 v117, 0, v117
	v_pk_mul_f32 v[106:107], v[106:107], v[178:179] op_sel_hi:[1,0]
	v_cndmask_b32_e32 v180, v183, v180, vcc
	v_div_scale_f32 v183, s[0:1], v180, v180, 1.0
	v_rcp_f32_e32 v184, v183
	v_mul_f32_e32 v118, v118, v118
	v_mul_f32_e32 v117, v117, v117
	v_pk_mul_f32 v[110:111], v[110:111], v[178:179] op_sel_hi:[1,0]
	v_fma_f32 v185, -v183, v184, 1.0
	v_fmac_f32_e32 v184, v185, v184
	v_div_scale_f32 v185, vcc, 1.0, v180, 1.0
	v_mul_f32_e32 v186, v185, v184
	v_fma_f32 v187, -v183, v186, v185
	v_fmac_f32_e32 v186, v187, v184
	v_fma_f32 v183, -v183, v186, v185
	v_div_fmas_f32 v183, v183, v184, v186
	v_mov_b32_e32 v184, v147
	v_mov_b32_e32 v185, v148
	v_mov_b32_e32 v147, v149
	v_pk_add_f32 v[146:147], v[184:185], v[146:147]
	v_div_fixup_f32 v180, v183, v180, 1.0
	ds_write_b32 v232, v180 offset:128
	v_add_f32_e32 v146, v146, v147
	v_fmamk_f32 v146, v146, 0x3a800000, v234
	v_cmp_gt_f32_e32 vcc, s4, v146
	v_mul_f32_e32 v147, 0x4f800000, v146
	v_pk_mul_f32 v[108:109], v[108:109], v[178:179] op_sel_hi:[1,0]
	v_cndmask_b32_e32 v146, v146, v147, vcc
	v_sqrt_f32_e32 v147, v146
	v_max_f32_e32 v106, 0, v106
	v_pk_mul_f32 v[112:113], v[112:113], v[178:179] op_sel_hi:[1,0]
	v_max_f32_e32 v107, 0, v107
	v_add_u32_e32 v148, -1, v147
	v_fma_f32 v149, -v148, v147, v146
	v_cmp_ge_f32_e64 s[0:1], 0, v149
	v_add_u32_e32 v149, 1, v147
	v_max_f32_e32 v108, 0, v108
	v_cndmask_b32_e64 v148, v147, v148, s[0:1]
	v_fma_f32 v147, -v149, v147, v146
	v_cmp_lt_f32_e64 s[0:1], 0, v147
	v_max_f32_e32 v110, 0, v110
	v_max_f32_e32 v109, 0, v109
	v_cndmask_b32_e64 v147, v148, v149, s[0:1]
	v_mul_f32_e32 v148, 0x37800000, v147
	v_cndmask_b32_e32 v147, v147, v148, vcc
	v_cmp_class_f32_e32 vcc, v146, v235
	v_pk_mul_f32 v[100:101], v[100:101], v[178:179] op_sel_hi:[1,0]
	v_pk_mul_f32 v[98:99], v[98:99], v[178:179] op_sel_hi:[1,0]
	v_cndmask_b32_e32 v146, v147, v146, vcc
	v_div_scale_f32 v147, s[0:1], v146, v146, 1.0
	v_rcp_f32_e32 v148, v147
	v_mul_f32_e32 v110, v110, v110
	v_mul_f32_e32 v109, v109, v109
	v_pk_mul_f32 v[104:105], v[104:105], v[178:179] op_sel_hi:[1,0]
	v_fma_f32 v149, -v147, v148, 1.0
	v_fmac_f32_e32 v148, v149, v148
	v_div_scale_f32 v149, vcc, 1.0, v146, 1.0
	v_mul_f32_e32 v183, v149, v148
	v_fma_f32 v184, -v147, v183, v149
	v_fmac_f32_e32 v183, v184, v148
	v_fma_f32 v147, -v147, v183, v149
	v_div_fmas_f32 v147, v147, v148, v183
	v_mov_b32_e32 v148, v143
	v_mov_b32_e32 v149, v144
	v_mov_b32_e32 v143, v145
	v_pk_add_f32 v[142:143], v[148:149], v[142:143]
	v_div_fixup_f32 v146, v147, v146, 1.0
	ds_write_b32 v232, v146 offset:192
	v_add_f32_e32 v142, v142, v143
	v_fmamk_f32 v142, v142, 0x3a800000, v234
	v_cmp_gt_f32_e32 vcc, s4, v142
	v_mul_f32_e32 v143, 0x4f800000, v142
	v_pk_mul_f32 v[102:103], v[102:103], v[178:179] op_sel_hi:[1,0]
	v_cndmask_b32_e32 v142, v142, v143, vcc
	v_sqrt_f32_e32 v143, v142
	v_max_f32_e32 v98, 0, v98
	v_max_f32_e32 v99, 0, v99
	v_max_f32_e32 v100, 0, v100
	v_add_u32_e32 v144, -1, v143
	v_fma_f32 v145, -v144, v143, v142
	v_cmp_ge_f32_e64 s[0:1], 0, v145
	v_add_u32_e32 v145, 1, v143
	v_max_f32_e32 v102, 0, v102
	v_cndmask_b32_e64 v144, v143, v144, s[0:1]
	v_fma_f32 v143, -v145, v143, v142
	v_cmp_lt_f32_e64 s[0:1], 0, v143
	v_max_f32_e32 v101, 0, v101
	v_pk_mul_f32 v[90:91], v[90:91], v[180:181] op_sel_hi:[1,0]
	v_cndmask_b32_e64 v143, v144, v145, s[0:1]
	v_mul_f32_e32 v144, 0x37800000, v143
	v_cndmask_b32_e32 v143, v143, v144, vcc
	v_cmp_class_f32_e32 vcc, v142, v235
	v_mul_f32_e32 v102, v102, v102
	v_mul_f32_e32 v101, v101, v101
	v_cndmask_b32_e32 v142, v143, v142, vcc
	v_div_scale_f32 v143, s[0:1], v142, v142, 1.0
	v_rcp_f32_e32 v144, v143
	v_pk_mul_f32 v[94:95], v[94:95], v[180:181] op_sel_hi:[1,0]
	v_pk_mul_f32 v[92:93], v[92:93], v[180:181] op_sel_hi:[1,0]
	v_max_f32_e32 v90, 0, v90
	v_fma_f32 v145, -v143, v144, 1.0
	v_fmac_f32_e32 v144, v145, v144
	v_div_scale_f32 v145, vcc, 1.0, v142, 1.0
	v_mul_f32_e32 v147, v145, v144
	v_fma_f32 v148, -v143, v147, v145
	v_fmac_f32_e32 v147, v148, v144
	v_fma_f32 v143, -v143, v147, v145
	v_div_fmas_f32 v143, v143, v144, v147
	v_mov_b32_e32 v144, v139
	v_mov_b32_e32 v145, v140
	v_mov_b32_e32 v139, v141
	v_pk_add_f32 v[138:139], v[144:145], v[138:139]
	v_div_fixup_f32 v142, v143, v142, 1.0
	ds_write_b32 v232, v142 offset:512
	v_add_f32_e32 v138, v138, v139
	v_fmamk_f32 v138, v138, 0x3a800000, v234
	v_cmp_gt_f32_e32 vcc, s4, v138
	v_mul_f32_e32 v139, 0x4f800000, v138
	v_pk_mul_f32 v[96:97], v[96:97], v[180:181] op_sel_hi:[1,0]
	v_cndmask_b32_e32 v138, v138, v139, vcc
	v_sqrt_f32_e32 v139, v138
	v_max_f32_e32 v91, 0, v91
	v_max_f32_e32 v92, 0, v92
	v_max_f32_e32 v94, 0, v94
	v_add_u32_e32 v140, -1, v139
	v_fma_f32 v141, -v140, v139, v138
	v_cmp_ge_f32_e64 s[0:1], 0, v141
	v_add_u32_e32 v141, 1, v139
	v_max_f32_e32 v93, 0, v93
	v_cndmask_b32_e64 v140, v139, v140, s[0:1]
	v_fma_f32 v139, -v141, v139, v138
	v_cmp_lt_f32_e64 s[0:1], 0, v139
	v_pk_mul_f32 v[84:85], v[84:85], v[180:181] op_sel_hi:[1,0]
	v_pk_mul_f32 v[82:83], v[82:83], v[180:181] op_sel_hi:[1,0]
	v_cndmask_b32_e64 v139, v140, v141, s[0:1]
	v_mul_f32_e32 v140, 0x37800000, v139
	v_cndmask_b32_e32 v139, v139, v140, vcc
	v_cmp_class_f32_e32 vcc, v138, v235
	v_mul_f32_e32 v94, v94, v94
	v_mul_f32_e32 v93, v93, v93
	v_cndmask_b32_e32 v138, v139, v138, vcc
	v_div_scale_f32 v139, s[0:1], v138, v138, 1.0
	v_rcp_f32_e32 v140, v139
	v_pk_mul_f32 v[88:89], v[88:89], v[180:181] op_sel_hi:[1,0]
	v_pk_mul_f32 v[86:87], v[86:87], v[180:181] op_sel_hi:[1,0]
	v_max_f32_e32 v82, 0, v82
	v_fma_f32 v141, -v139, v140, 1.0
	v_fmac_f32_e32 v140, v141, v140
	v_div_scale_f32 v141, vcc, 1.0, v138, 1.0
	v_mul_f32_e32 v143, v141, v140
	v_fma_f32 v144, -v139, v143, v141
	v_fmac_f32_e32 v143, v144, v140
	v_fma_f32 v139, -v139, v143, v141
	v_div_fmas_f32 v139, v139, v140, v143
	v_mov_b32_e32 v140, v135
	v_mov_b32_e32 v141, v136
	v_mov_b32_e32 v135, v137
	v_pk_add_f32 v[134:135], v[140:141], v[134:135]
	v_div_fixup_f32 v138, v139, v138, 1.0
	ds_write_b32 v232, v138 offset:576
	v_add_f32_e32 v134, v134, v135
	v_fmamk_f32 v134, v134, 0x3a800000, v234
	v_cmp_gt_f32_e32 vcc, s4, v134
	v_mul_f32_e32 v135, 0x4f800000, v134
	v_max_f32_e32 v83, 0, v83
	v_cndmask_b32_e32 v134, v134, v135, vcc
	v_sqrt_f32_e32 v135, v134
	v_max_f32_e32 v84, 0, v84
	v_max_f32_e32 v86, 0, v86
	v_max_f32_e32 v85, 0, v85
	v_add_u32_e32 v136, -1, v135
	v_fma_f32 v137, -v136, v135, v134
	v_cmp_ge_f32_e64 s[0:1], 0, v137
	v_add_u32_e32 v137, 1, v135
	v_pk_mul_f32 v[74:75], v[74:75], v[146:147] op_sel_hi:[1,0]
	v_cndmask_b32_e64 v136, v135, v136, s[0:1]
	v_fma_f32 v135, -v137, v135, v134
	v_cmp_lt_f32_e64 s[0:1], 0, v135
	v_mul_f32_e32 v86, v86, v86
	v_mul_f32_e32 v85, v85, v85
	v_cndmask_b32_e64 v135, v136, v137, s[0:1]
	v_mul_f32_e32 v136, 0x37800000, v135
	v_cndmask_b32_e32 v135, v135, v136, vcc
	v_cmp_class_f32_e32 vcc, v134, v235
	v_pk_mul_f32 v[78:79], v[78:79], v[146:147] op_sel_hi:[1,0]
	v_pk_mul_f32 v[76:77], v[76:77], v[146:147] op_sel_hi:[1,0]
	v_cndmask_b32_e32 v134, v135, v134, vcc
	v_div_scale_f32 v135, s[0:1], v134, v134, 1.0
	v_rcp_f32_e32 v136, v135
	v_max_f32_e32 v74, 0, v74
	v_pk_mul_f32 v[80:81], v[80:81], v[146:147] op_sel_hi:[1,0]
	v_max_f32_e32 v75, 0, v75
	v_fma_f32 v137, -v135, v136, 1.0
	v_fmac_f32_e32 v136, v137, v136
	v_div_scale_f32 v137, vcc, 1.0, v134, 1.0
	v_mul_f32_e32 v139, v137, v136
	v_fma_f32 v140, -v135, v139, v137
	v_fmac_f32_e32 v139, v140, v136
	v_fma_f32 v135, -v135, v139, v137
	v_div_fmas_f32 v135, v135, v136, v139
	v_mov_b32_e32 v136, v131
	v_mov_b32_e32 v137, v132
	v_mov_b32_e32 v131, v133
	v_pk_add_f32 v[130:131], v[136:137], v[130:131]
	v_div_fixup_f32 v134, v135, v134, 1.0
	ds_write_b32 v232, v134 offset:640
	v_add_f32_e32 v130, v130, v131
	v_fmamk_f32 v130, v130, 0x3a800000, v234
	v_cmp_gt_f32_e32 vcc, s4, v130
	v_mul_f32_e32 v131, 0x4f800000, v130
	v_max_f32_e32 v76, 0, v76
	v_cndmask_b32_e32 v130, v130, v131, vcc
	v_sqrt_f32_e32 v131, v130
	v_max_f32_e32 v78, 0, v78
	v_max_f32_e32 v77, 0, v77
	v_pk_mul_f32 v[68:69], v[68:69], v[146:147] op_sel_hi:[1,0]
	v_add_u32_e32 v132, -1, v131
	v_fma_f32 v133, -v132, v131, v130
	v_cmp_ge_f32_e64 s[0:1], 0, v133
	v_add_u32_e32 v133, 1, v131
	v_pk_mul_f32 v[66:67], v[66:67], v[146:147] op_sel_hi:[1,0]
	v_cndmask_b32_e64 v132, v131, v132, s[0:1]
	v_fma_f32 v131, -v133, v131, v130
	v_cmp_lt_f32_e64 s[0:1], 0, v131
	v_mul_f32_e32 v78, v78, v78
	v_mul_f32_e32 v77, v77, v77
	v_cndmask_b32_e64 v131, v132, v133, s[0:1]
	v_mul_f32_e32 v132, 0x37800000, v131
	v_cndmask_b32_e32 v131, v131, v132, vcc
	v_cmp_class_f32_e32 vcc, v130, v235
	v_pk_mul_f32 v[72:73], v[72:73], v[146:147] op_sel_hi:[1,0]
	v_pk_mul_f32 v[70:71], v[70:71], v[146:147] op_sel_hi:[1,0]
	v_cndmask_b32_e32 v130, v131, v130, vcc
	v_div_scale_f32 v131, s[0:1], v130, v130, 1.0
	v_rcp_f32_e32 v132, v131
	v_readlane_b32 s0, v249, 30
	v_readlane_b32 s1, v249, 31
	v_max_f32_e32 v66, 0, v66
	v_fma_f32 v133, -v131, v132, 1.0
	v_fmac_f32_e32 v132, v133, v132
	v_div_scale_f32 v133, vcc, 1.0, v130, 1.0
	v_mul_f32_e32 v135, v133, v132
	v_fma_f32 v136, -v131, v135, v133
	v_fmac_f32_e32 v135, v136, v132
	v_fma_f32 v131, -v131, v135, v133
	v_div_fmas_f32 v131, v131, v132, v135
	v_lshl_add_u32 v132, s52, 8, v181
	v_div_fixup_f32 v130, v131, v130, 1.0
	ds_write_b32 v232, v130 offset:704
	v_ashrrev_i32_e32 v133, 31, v132
	v_lshlrev_b64 v[136:137], 13, v[174:175]
	v_mul_f32_e32 v131, v122, v122
	v_max_f32_e32 v122, 0, v127
	v_lshl_add_u64 v[136:137], s[0:1], 0, v[136:137]
	v_lshlrev_b64 v[132:133], 1, v[132:133]
	v_mul_f32_e32 v122, v122, v122
	v_mul_f32_e32 v127, v123, v123
	v_max_f32_e32 v123, 0, v128
	v_mul_f32_e32 v128, v124, v124
	v_max_f32_e32 v124, 0, v129
	v_lshl_add_u64 v[136:137], v[136:137], 0, v[132:133]
	v_mul_f32_e32 v123, v123, v123
	v_mul_f32_e32 v124, v124, v124
	v_cvt_pk_bf16_f32 v122, v126, v122
	v_cvt_pk_bf16_f32 v123, v123, v124
	v_cvt_pk_bf16_f32 v124, v131, v127
	v_cvt_pk_bf16_f32 v125, v128, v125
	global_store_dwordx4 v[136:137], v[122:125], off nt
	v_max_f32_e32 v67, 0, v67
	v_max_f32_e32 v68, 0, v68
	v_mul_f32_e32 v122, v114, v114
	v_max_f32_e32 v114, 0, v119
	v_mul_f32_e32 v119, v115, v115
	v_max_f32_e32 v115, 0, v120
	v_mul_f32_e32 v120, v116, v116
	v_max_f32_e32 v116, 0, v121
	v_mul_f32_e32 v114, v114, v114
	v_mul_f32_e32 v115, v115, v115
	v_mul_f32_e32 v116, v116, v116
	v_cvt_pk_bf16_f32 v114, v118, v114
	v_cvt_pk_bf16_f32 v115, v115, v116
	v_cvt_pk_bf16_f32 v116, v122, v119
	v_cvt_pk_bf16_f32 v117, v120, v117
	global_store_dwordx4 v[136:137], v[114:117], off offset:256 nt
	v_max_f32_e32 v70, 0, v70
	v_max_f32_e32 v69, 0, v69
	v_lshlrev_b64 v[114:115], 13, v[172:173]
	v_mul_f32_e32 v116, v106, v106
	v_max_f32_e32 v106, 0, v111
	v_lshl_add_u64 v[114:115], s[0:1], 0, v[114:115]
	v_mul_f32_e32 v106, v106, v106
	v_mul_f32_e32 v111, v107, v107
	v_max_f32_e32 v107, 0, v112
	v_mul_f32_e32 v112, v108, v108
	v_max_f32_e32 v108, 0, v113
	v_lshl_add_u64 v[114:115], v[114:115], 0, v[132:133]
	v_mul_f32_e32 v107, v107, v107
	v_mul_f32_e32 v108, v108, v108
	v_cvt_pk_bf16_f32 v106, v110, v106
	v_cvt_pk_bf16_f32 v107, v107, v108
	v_cvt_pk_bf16_f32 v108, v116, v111
	v_cvt_pk_bf16_f32 v109, v112, v109
	global_store_dwordx4 v[114:115], v[106:109], off nt
	v_pk_mul_f32 v[56:57], v[56:57], v[142:143] op_sel_hi:[1,0]
	v_mul_f32_e32 v70, v70, v70
	v_mul_f32_e32 v106, v98, v98
	v_max_f32_e32 v98, 0, v103
	v_mul_f32_e32 v103, v99, v99
	v_max_f32_e32 v99, 0, v104
	v_mul_f32_e32 v104, v100, v100
	v_max_f32_e32 v100, 0, v105
	v_mul_f32_e32 v98, v98, v98
	v_mul_f32_e32 v99, v99, v99
	v_mul_f32_e32 v100, v100, v100
	v_cvt_pk_bf16_f32 v98, v102, v98
	v_cvt_pk_bf16_f32 v99, v99, v100
	v_cvt_pk_bf16_f32 v100, v106, v103
	v_cvt_pk_bf16_f32 v101, v104, v101
	global_store_dwordx4 v[114:115], v[98:101], off offset:256 nt
	v_mul_f32_e32 v69, v69, v69
	v_pk_mul_f32 v[60:61], v[60:61], v[142:143] op_sel_hi:[1,0]
	v_lshlrev_b64 v[98:99], 13, v[170:171]
	v_mul_f32_e32 v100, v90, v90
	v_max_f32_e32 v90, 0, v95
	v_lshl_add_u64 v[98:99], s[0:1], 0, v[98:99]
	v_mul_f32_e32 v90, v90, v90
	v_mul_f32_e32 v95, v91, v91
	v_max_f32_e32 v91, 0, v96
	v_mul_f32_e32 v96, v92, v92
	v_max_f32_e32 v92, 0, v97
	v_lshl_add_u64 v[98:99], v[98:99], 0, v[132:133]
	v_mul_f32_e32 v91, v91, v91
	v_mul_f32_e32 v92, v92, v92
	v_cvt_pk_bf16_f32 v90, v94, v90
	v_cvt_pk_bf16_f32 v91, v91, v92
	v_cvt_pk_bf16_f32 v92, v100, v95
	v_cvt_pk_bf16_f32 v93, v96, v93
	global_store_dwordx4 v[98:99], v[90:93], off nt
	v_pk_mul_f32 v[58:59], v[58:59], v[142:143] op_sel_hi:[1,0]
	v_max_f32_e32 v56, 0, v56
	v_mul_f32_e32 v90, v82, v82
	v_max_f32_e32 v82, 0, v87
	v_mul_f32_e32 v87, v83, v83
	v_max_f32_e32 v83, 0, v88
	v_mul_f32_e32 v88, v84, v84
	v_max_f32_e32 v84, 0, v89
	v_mul_f32_e32 v82, v82, v82
	v_mul_f32_e32 v83, v83, v83
	v_mul_f32_e32 v84, v84, v84
	v_cvt_pk_bf16_f32 v82, v86, v82
	v_cvt_pk_bf16_f32 v83, v83, v84
	v_cvt_pk_bf16_f32 v84, v90, v87
	v_cvt_pk_bf16_f32 v85, v88, v85
	global_store_dwordx4 v[98:99], v[82:85], off offset:256 nt
	v_pk_mul_f32 v[62:63], v[62:63], v[142:143] op_sel_hi:[1,0]
	v_max_f32_e32 v57, 0, v57
	v_lshlrev_b64 v[82:83], 13, v[168:169]
	v_mul_f32_e32 v84, v74, v74
	v_max_f32_e32 v74, 0, v79
	v_lshl_add_u64 v[82:83], s[0:1], 0, v[82:83]
	v_mul_f32_e32 v74, v74, v74
	v_mul_f32_e32 v79, v75, v75
	v_max_f32_e32 v75, 0, v80
	v_mul_f32_e32 v80, v76, v76
	v_max_f32_e32 v76, 0, v81
	v_lshl_add_u64 v[82:83], v[82:83], 0, v[132:133]
	v_mul_f32_e32 v75, v75, v75
	v_mul_f32_e32 v76, v76, v76
	v_cvt_pk_bf16_f32 v74, v78, v74
	v_cvt_pk_bf16_f32 v75, v75, v76
	v_cvt_pk_bf16_f32 v76, v84, v79
	v_cvt_pk_bf16_f32 v77, v80, v77
	global_store_dwordx4 v[82:83], v[74:77], off nt
	v_max_f32_e32 v58, 0, v58
	v_max_f32_e32 v60, 0, v60
	v_mul_f32_e32 v74, v66, v66
	v_max_f32_e32 v66, 0, v71
	v_mul_f32_e32 v71, v67, v67
	v_max_f32_e32 v67, 0, v72
	v_mul_f32_e32 v72, v68, v68
	v_max_f32_e32 v68, 0, v73
	v_mul_f32_e32 v66, v66, v66
	v_mul_f32_e32 v67, v67, v67
	v_mul_f32_e32 v68, v68, v68
	v_cvt_pk_bf16_f32 v66, v70, v66
	v_cvt_pk_bf16_f32 v67, v67, v68
	v_cvt_pk_bf16_f32 v68, v74, v71
	v_cvt_pk_bf16_f32 v69, v72, v69
	global_store_dwordx4 v[82:83], v[66:69], off offset:256 nt
	v_max_f32_e32 v59, 0, v59
	v_pk_mul_f32 v[50:51], v[50:51], v[142:143] op_sel_hi:[1,0]
	v_lshlrev_b64 v[66:67], 13, v[166:167]
	v_mul_f32_e32 v68, v56, v56
	v_max_f32_e32 v56, 0, v61
	v_lshl_add_u64 v[66:67], s[0:1], 0, v[66:67]
	v_mul_f32_e32 v56, v56, v56
	v_mul_f32_e32 v61, v57, v57
	v_max_f32_e32 v57, 0, v62
	v_mul_f32_e32 v62, v58, v58
	v_max_f32_e32 v58, 0, v63
	v_pk_mul_f32 v[48:49], v[48:49], v[142:143] op_sel_hi:[1,0]
	v_lshl_add_u64 v[66:67], v[66:67], 0, v[132:133]
	v_mul_f32_e32 v60, v60, v60
	v_mul_f32_e32 v57, v57, v57
	v_mul_f32_e32 v58, v58, v58
	v_mul_f32_e32 v59, v59, v59
	v_cvt_pk_bf16_f32 v56, v60, v56
	v_pk_mul_f32 v[54:55], v[54:55], v[142:143] op_sel_hi:[1,0]
	v_pk_mul_f32 v[52:53], v[52:53], v[142:143] op_sel_hi:[1,0]
	v_max_f32_e32 v48, 0, v48
	v_max_f32_e32 v49, 0, v49
	v_max_f32_e32 v50, 0, v50
	v_cvt_pk_bf16_f32 v57, v57, v58
	v_cvt_pk_bf16_f32 v58, v68, v61
	v_cvt_pk_bf16_f32 v59, v62, v59
	global_store_dwordx4 v[66:67], v[56:59], off nt
	v_max_f32_e32 v52, 0, v52
	v_max_f32_e32 v51, 0, v51
	v_mul_f32_e32 v56, v48, v48
	v_max_f32_e32 v48, 0, v53
	v_mul_f32_e32 v53, v49, v49
	v_max_f32_e32 v49, 0, v54
	v_mul_f32_e32 v54, v50, v50
	v_max_f32_e32 v50, 0, v55
	v_mul_f32_e32 v48, v48, v48
	v_mul_f32_e32 v49, v49, v49
	v_mul_f32_e32 v50, v50, v50
	v_pk_mul_f32 v[40:41], v[40:41], v[138:139] op_sel_hi:[1,0]
	v_mul_f32_e32 v52, v52, v52
	v_mul_f32_e32 v51, v51, v51
	v_cvt_pk_bf16_f32 v48, v52, v48
	v_cvt_pk_bf16_f32 v49, v49, v50
	v_cvt_pk_bf16_f32 v50, v56, v53
	v_pk_mul_f32 v[44:45], v[44:45], v[138:139] op_sel_hi:[1,0]
	v_pk_mul_f32 v[42:43], v[42:43], v[138:139] op_sel_hi:[1,0]
	v_max_f32_e32 v40, 0, v40
	v_cvt_pk_bf16_f32 v51, v54, v51
	global_store_dwordx4 v[66:67], v[48:51], off offset:256 nt
	v_pk_mul_f32 v[46:47], v[46:47], v[138:139] op_sel_hi:[1,0]
	v_max_f32_e32 v41, 0, v41
	v_lshlrev_b64 v[48:49], 13, v[164:165]
	v_mul_f32_e32 v50, v40, v40
	v_max_f32_e32 v40, 0, v45
	v_max_f32_e32 v42, 0, v42
	v_lshl_add_u64 v[48:49], s[0:1], 0, v[48:49]
	v_max_f32_e32 v44, 0, v44
	v_mul_f32_e32 v40, v40, v40
	v_mul_f32_e32 v45, v41, v41
	v_max_f32_e32 v41, 0, v46
	v_mul_f32_e32 v46, v42, v42
	v_max_f32_e32 v42, 0, v47
	v_max_f32_e32 v43, 0, v43
	v_pk_mul_f32 v[34:35], v[34:35], v[138:139] op_sel_hi:[1,0]
	v_pk_mul_f32 v[32:33], v[32:33], v[138:139] op_sel_hi:[1,0]
	v_lshl_add_u64 v[48:49], v[48:49], 0, v[132:133]
	v_mul_f32_e32 v44, v44, v44
	v_mul_f32_e32 v41, v41, v41
	v_mul_f32_e32 v42, v42, v42
	v_mul_f32_e32 v43, v43, v43
	v_cvt_pk_bf16_f32 v40, v44, v40
	v_pk_mul_f32 v[38:39], v[38:39], v[138:139] op_sel_hi:[1,0]
	v_pk_mul_f32 v[36:37], v[36:37], v[138:139] op_sel_hi:[1,0]
	v_max_f32_e32 v32, 0, v32
	v_max_f32_e32 v33, 0, v33
	v_max_f32_e32 v34, 0, v34
	v_cvt_pk_bf16_f32 v41, v41, v42
	v_cvt_pk_bf16_f32 v42, v50, v45
	v_cvt_pk_bf16_f32 v43, v46, v43
	global_store_dwordx4 v[48:49], v[40:43], off nt
	v_max_f32_e32 v36, 0, v36
	v_max_f32_e32 v35, 0, v35
	v_mul_f32_e32 v40, v32, v32
	v_max_f32_e32 v32, 0, v37
	v_mul_f32_e32 v37, v33, v33
	v_max_f32_e32 v33, 0, v38
	v_mul_f32_e32 v38, v34, v34
	v_max_f32_e32 v34, 0, v39
	v_mul_f32_e32 v32, v32, v32
	v_mul_f32_e32 v33, v33, v33
	v_mul_f32_e32 v34, v34, v34
	v_pk_mul_f32 v[24:25], v[24:25], v[134:135] op_sel_hi:[1,0]
	v_mul_f32_e32 v36, v36, v36
	v_mul_f32_e32 v35, v35, v35
	v_cvt_pk_bf16_f32 v32, v36, v32
	v_cvt_pk_bf16_f32 v33, v33, v34
	v_cvt_pk_bf16_f32 v34, v40, v37
	v_pk_mul_f32 v[28:29], v[28:29], v[134:135] op_sel_hi:[1,0]
	v_pk_mul_f32 v[26:27], v[26:27], v[134:135] op_sel_hi:[1,0]
	v_max_f32_e32 v24, 0, v24
	v_cvt_pk_bf16_f32 v35, v38, v35
	global_store_dwordx4 v[48:49], v[32:35], off offset:256 nt
	v_pk_mul_f32 v[30:31], v[30:31], v[134:135] op_sel_hi:[1,0]
	v_max_f32_e32 v25, 0, v25
	v_lshlrev_b64 v[32:33], 13, v[162:163]
	v_mul_f32_e32 v34, v24, v24
	v_max_f32_e32 v24, 0, v29
	v_max_f32_e32 v26, 0, v26
	v_lshl_add_u64 v[32:33], s[0:1], 0, v[32:33]
	v_max_f32_e32 v28, 0, v28
	v_mul_f32_e32 v24, v24, v24
	v_mul_f32_e32 v29, v25, v25
	v_max_f32_e32 v25, 0, v30
	v_mul_f32_e32 v30, v26, v26
	v_max_f32_e32 v26, 0, v31
	v_max_f32_e32 v27, 0, v27
	v_pk_mul_f32 v[18:19], v[18:19], v[134:135] op_sel_hi:[1,0]
	v_pk_mul_f32 v[16:17], v[16:17], v[134:135] op_sel_hi:[1,0]
	v_lshl_add_u64 v[32:33], v[32:33], 0, v[132:133]
	v_mul_f32_e32 v28, v28, v28
	v_mul_f32_e32 v25, v25, v25
	v_mul_f32_e32 v26, v26, v26
	v_mul_f32_e32 v27, v27, v27
	v_cvt_pk_bf16_f32 v24, v28, v24
	v_pk_mul_f32 v[22:23], v[22:23], v[134:135] op_sel_hi:[1,0]
	v_pk_mul_f32 v[20:21], v[20:21], v[134:135] op_sel_hi:[1,0]
	v_max_f32_e32 v16, 0, v16
	v_max_f32_e32 v17, 0, v17
	v_max_f32_e32 v18, 0, v18
	v_cvt_pk_bf16_f32 v25, v25, v26
	v_cvt_pk_bf16_f32 v26, v34, v29
	v_cvt_pk_bf16_f32 v27, v30, v27
	global_store_dwordx4 v[32:33], v[24:27], off nt
	v_max_f32_e32 v20, 0, v20
	v_max_f32_e32 v19, 0, v19
	v_mul_f32_e32 v24, v16, v16
	v_max_f32_e32 v16, 0, v21
	v_mul_f32_e32 v21, v17, v17
	v_max_f32_e32 v17, 0, v22
	v_mul_f32_e32 v22, v18, v18
	v_max_f32_e32 v18, 0, v23
	v_mul_f32_e32 v16, v16, v16
	v_mul_f32_e32 v17, v17, v17
	v_mul_f32_e32 v18, v18, v18
	v_pk_mul_f32 v[8:9], v[8:9], v[130:131] op_sel_hi:[1,0]
	v_mul_f32_e32 v20, v20, v20
	v_mul_f32_e32 v19, v19, v19
	v_cvt_pk_bf16_f32 v16, v20, v16
	v_cvt_pk_bf16_f32 v17, v17, v18
	v_cvt_pk_bf16_f32 v18, v24, v21
	v_pk_mul_f32 v[12:13], v[12:13], v[130:131] op_sel_hi:[1,0]
	v_pk_mul_f32 v[10:11], v[10:11], v[130:131] op_sel_hi:[1,0]
	v_max_f32_e32 v8, 0, v8
	v_cvt_pk_bf16_f32 v19, v22, v19
	global_store_dwordx4 v[32:33], v[16:19], off offset:256 nt
	v_pk_mul_f32 v[14:15], v[14:15], v[130:131] op_sel_hi:[1,0]
	v_max_f32_e32 v9, 0, v9
	v_lshlrev_b64 v[16:17], 13, v[160:161]
	v_mul_f32_e32 v18, v8, v8
	v_max_f32_e32 v8, 0, v13
	v_max_f32_e32 v10, 0, v10
	v_lshl_add_u64 v[16:17], s[0:1], 0, v[16:17]
	v_max_f32_e32 v12, 0, v12
	v_mul_f32_e32 v8, v8, v8
	v_mul_f32_e32 v13, v9, v9
	v_max_f32_e32 v9, 0, v14
	v_mul_f32_e32 v14, v10, v10
	v_max_f32_e32 v10, 0, v15
	v_max_f32_e32 v11, 0, v11
	v_pk_mul_f32 v[2:3], v[2:3], v[130:131] op_sel_hi:[1,0]
	v_pk_mul_f32 v[0:1], v[0:1], v[130:131] op_sel_hi:[1,0]
	v_lshl_add_u64 v[16:17], v[16:17], 0, v[132:133]
	v_mul_f32_e32 v12, v12, v12
	v_mul_f32_e32 v9, v9, v9
	v_mul_f32_e32 v10, v10, v10
	v_mul_f32_e32 v11, v11, v11
	v_cvt_pk_bf16_f32 v8, v12, v8
	v_pk_mul_f32 v[6:7], v[6:7], v[130:131] op_sel_hi:[1,0]
	v_pk_mul_f32 v[4:5], v[4:5], v[130:131] op_sel_hi:[1,0]
	v_max_f32_e32 v0, 0, v0
	v_max_f32_e32 v1, 0, v1
	v_max_f32_e32 v2, 0, v2
	v_cvt_pk_bf16_f32 v9, v9, v10
	v_cvt_pk_bf16_f32 v10, v18, v13
	v_cvt_pk_bf16_f32 v11, v14, v11
	global_store_dwordx4 v[16:17], v[8:11], off nt
	v_max_f32_e32 v3, 0, v3
	v_max_f32_e32 v4, 0, v4
	v_mul_f32_e32 v8, v0, v0
	v_max_f32_e32 v0, 0, v5
	v_mul_f32_e32 v5, v1, v1
	v_max_f32_e32 v1, 0, v6
	v_mul_f32_e32 v6, v2, v2
	v_max_f32_e32 v2, 0, v7
	v_mul_f32_e32 v0, v0, v0
	v_mul_f32_e32 v1, v1, v1
	v_mul_f32_e32 v2, v2, v2
	v_mul_f32_e32 v3, v3, v3
	s_mov_b64 s[0:1], -1
	s_andn2_b64 vcc, exec, s[42:43]
	v_mul_f32_e32 v4, v4, v4
	v_cvt_pk_bf16_f32 v0, v4, v0
	v_cvt_pk_bf16_f32 v1, v1, v2
	v_cvt_pk_bf16_f32 v2, v8, v5
	v_cvt_pk_bf16_f32 v3, v6, v3
	global_store_dwordx4 v[16:17], v[0:3], off offset:256 nt
	s_mov_b32 s32, 1

.Lff1_cached:
	v_lshlrev_b32_e32 v232, 2, v177
	v_add_u32_e32 v232, 0x20000, v232
	ds_read_b32 v176, v232 offset:0
	ds_read_b32 v178, v232 offset:64
	ds_read_b32 v180, v232 offset:128
	ds_read_b32 v146, v232 offset:192
	ds_read_b32 v142, v232 offset:512
	ds_read_b32 v138, v232 offset:576
	ds_read_b32 v134, v232 offset:640
	ds_read_b32 v130, v232 offset:704
	s_waitcnt lgkmcnt(0)
	v_lshl_add_u32 v174, s4, 8, v177
	v_or_b32_e32 v172, 16, v174
	v_ashrrev_i32_e32 v175, 31, v174
	v_ashrrev_i32_e32 v173, 31, v172
	v_or_b32_e32 v170, 32, v174
	v_or_b32_e32 v168, 48, v174
	v_ashrrev_i32_e32 v171, 31, v170
	v_ashrrev_i32_e32 v169, 31, v168
	v_add_u32_e32 v166, 0x80, v174
	v_add_u32_e32 v164, 0x90, v174
	v_ashrrev_i32_e32 v167, 31, v166
	v_ashrrev_i32_e32 v165, 31, v164
	v_add_u32_e32 v162, 0xa0, v174
	v_add_u32_e32 v160, 0xb0, v174
	v_ashrrev_i32_e32 v163, 31, v162
	v_ashrrev_i32_e32 v161, 31, v160
	s_nop 0
	s_waitcnt vmcnt(0)
	s_nop 0
	s_nop 0
	s_nop 0
	s_nop 1
	s_nop 1
	s_nop 0
	v_pk_mul_f32 v[122:123], v[122:123], v[176:177] op_sel_hi:[1,0]
	v_pk_mul_f32 v[126:127], v[126:127], v[176:177] op_sel_hi:[1,0]
	v_pk_mul_f32 v[124:125], v[124:125], v[176:177] op_sel_hi:[1,0]
	v_max_f32_e32 v122, 0, v122
	v_pk_mul_f32 v[128:129], v[128:129], v[176:177] op_sel_hi:[1,0]
	v_max_f32_e32 v123, 0, v123
	v_max_f32_e32 v124, 0, v124
	v_max_f32_e32 v126, 0, v126
	v_max_f32_e32 v125, 0, v125
	v_pk_mul_f32 v[116:117], v[116:117], v[176:177] op_sel_hi:[1,0]
	v_pk_mul_f32 v[114:115], v[114:115], v[176:177] op_sel_hi:[1,0]
	v_mul_f32_e32 v126, v126, v126
	v_mul_f32_e32 v125, v125, v125
	v_pk_mul_f32 v[120:121], v[120:121], v[176:177] op_sel_hi:[1,0]
	v_pk_mul_f32 v[118:119], v[118:119], v[176:177] op_sel_hi:[1,0]
	v_max_f32_e32 v114, 0, v114
	v_max_f32_e32 v115, 0, v115
	v_max_f32_e32 v116, 0, v116
	v_max_f32_e32 v118, 0, v118
	v_max_f32_e32 v117, 0, v117
	v_pk_mul_f32 v[106:107], v[106:107], v[178:179] op_sel_hi:[1,0]
	v_mul_f32_e32 v118, v118, v118
	v_mul_f32_e32 v117, v117, v117
	v_pk_mul_f32 v[110:111], v[110:111], v[178:179] op_sel_hi:[1,0]
	v_pk_mul_f32 v[108:109], v[108:109], v[178:179] op_sel_hi:[1,0]
	v_max_f32_e32 v106, 0, v106
	v_pk_mul_f32 v[112:113], v[112:113], v[178:179] op_sel_hi:[1,0]
	v_max_f32_e32 v107, 0, v107
	v_max_f32_e32 v108, 0, v108
	v_max_f32_e32 v110, 0, v110
	v_max_f32_e32 v109, 0, v109
	v_pk_mul_f32 v[100:101], v[100:101], v[178:179] op_sel_hi:[1,0]
	v_pk_mul_f32 v[98:99], v[98:99], v[178:179] op_sel_hi:[1,0]
	v_mul_f32_e32 v110, v110, v110
	v_mul_f32_e32 v109, v109, v109
	v_pk_mul_f32 v[104:105], v[104:105], v[178:179] op_sel_hi:[1,0]
	v_pk_mul_f32 v[102:103], v[102:103], v[178:179] op_sel_hi:[1,0]
	v_max_f32_e32 v98, 0, v98
	v_max_f32_e32 v99, 0, v99
	v_max_f32_e32 v100, 0, v100
	v_max_f32_e32 v102, 0, v102
	v_max_f32_e32 v101, 0, v101
	v_pk_mul_f32 v[90:91], v[90:91], v[180:181] op_sel_hi:[1,0]
	v_mul_f32_e32 v102, v102, v102
	v_mul_f32_e32 v101, v101, v101
	v_pk_mul_f32 v[94:95], v[94:95], v[180:181] op_sel_hi:[1,0]
	v_pk_mul_f32 v[92:93], v[92:93], v[180:181] op_sel_hi:[1,0]
	v_max_f32_e32 v90, 0, v90
	v_pk_mul_f32 v[96:97], v[96:97], v[180:181] op_sel_hi:[1,0]
	v_max_f32_e32 v91, 0, v91
	v_max_f32_e32 v92, 0, v92
	v_max_f32_e32 v94, 0, v94
	v_max_f32_e32 v93, 0, v93
	v_pk_mul_f32 v[84:85], v[84:85], v[180:181] op_sel_hi:[1,0]
	v_pk_mul_f32 v[82:83], v[82:83], v[180:181] op_sel_hi:[1,0]
	v_mul_f32_e32 v94, v94, v94
	v_mul_f32_e32 v93, v93, v93
	v_pk_mul_f32 v[88:89], v[88:89], v[180:181] op_sel_hi:[1,0]
	v_pk_mul_f32 v[86:87], v[86:87], v[180:181] op_sel_hi:[1,0]
	v_max_f32_e32 v82, 0, v82
	v_max_f32_e32 v83, 0, v83
	v_max_f32_e32 v84, 0, v84
	v_max_f32_e32 v86, 0, v86
	v_max_f32_e32 v85, 0, v85
	v_pk_mul_f32 v[74:75], v[74:75], v[146:147] op_sel_hi:[1,0]
	v_mul_f32_e32 v86, v86, v86
	v_mul_f32_e32 v85, v85, v85
	v_pk_mul_f32 v[78:79], v[78:79], v[146:147] op_sel_hi:[1,0]
	v_pk_mul_f32 v[76:77], v[76:77], v[146:147] op_sel_hi:[1,0]
	v_max_f32_e32 v74, 0, v74
	v_pk_mul_f32 v[80:81], v[80:81], v[146:147] op_sel_hi:[1,0]
	v_max_f32_e32 v75, 0, v75
	v_max_f32_e32 v76, 0, v76
	v_max_f32_e32 v78, 0, v78
	v_max_f32_e32 v77, 0, v77
	v_pk_mul_f32 v[68:69], v[68:69], v[146:147] op_sel_hi:[1,0]
	v_pk_mul_f32 v[66:67], v[66:67], v[146:147] op_sel_hi:[1,0]
	v_mul_f32_e32 v78, v78, v78
	v_mul_f32_e32 v77, v77, v77
	v_pk_mul_f32 v[72:73], v[72:73], v[146:147] op_sel_hi:[1,0]
	v_pk_mul_f32 v[70:71], v[70:71], v[146:147] op_sel_hi:[1,0]
	v_readlane_b32 s0, v249, 30
	v_readlane_b32 s1, v249, 31
	v_max_f32_e32 v66, 0, v66
	v_lshl_add_u32 v132, s52, 8, v181
	v_ashrrev_i32_e32 v133, 31, v132
	v_lshlrev_b64 v[136:137], 13, v[174:175]
	v_mul_f32_e32 v131, v122, v122
	v_max_f32_e32 v122, 0, v127
	v_lshl_add_u64 v[136:137], s[0:1], 0, v[136:137]
	v_lshlrev_b64 v[132:133], 1, v[132:133]
	v_mul_f32_e32 v122, v122, v122
	v_mul_f32_e32 v127, v123, v123
	v_max_f32_e32 v123, 0, v128
	v_mul_f32_e32 v128, v124, v124
	v_max_f32_e32 v124, 0, v129
	v_lshl_add_u64 v[136:137], v[136:137], 0, v[132:133]
	v_mul_f32_e32 v123, v123, v123
	v_mul_f32_e32 v124, v124, v124
	v_cvt_pk_bf16_f32 v122, v126, v122
	v_cvt_pk_bf16_f32 v123, v123, v124
	v_cvt_pk_bf16_f32 v124, v131, v127
	v_cvt_pk_bf16_f32 v125, v128, v125
	global_store_dwordx4 v[136:137], v[122:125], off nt
	v_max_f32_e32 v67, 0, v67
	v_max_f32_e32 v68, 0, v68
	v_mul_f32_e32 v122, v114, v114
	v_max_f32_e32 v114, 0, v119
	v_mul_f32_e32 v119, v115, v115
	v_max_f32_e32 v115, 0, v120
	v_mul_f32_e32 v120, v116, v116
	v_max_f32_e32 v116, 0, v121
	v_mul_f32_e32 v114, v114, v114
	v_mul_f32_e32 v115, v115, v115
	v_mul_f32_e32 v116, v116, v116
	v_cvt_pk_bf16_f32 v114, v118, v114
	v_cvt_pk_bf16_f32 v115, v115, v116
	v_cvt_pk_bf16_f32 v116, v122, v119
	v_cvt_pk_bf16_f32 v117, v120, v117
	global_store_dwordx4 v[136:137], v[114:117], off offset:256 nt
	v_max_f32_e32 v70, 0, v70
	v_max_f32_e32 v69, 0, v69
	v_lshlrev_b64 v[114:115], 13, v[172:173]
	v_mul_f32_e32 v116, v106, v106
	v_max_f32_e32 v106, 0, v111
	v_lshl_add_u64 v[114:115], s[0:1], 0, v[114:115]
	v_mul_f32_e32 v106, v106, v106
	v_mul_f32_e32 v111, v107, v107
	v_max_f32_e32 v107, 0, v112
	v_mul_f32_e32 v112, v108, v108
	v_max_f32_e32 v108, 0, v113
	v_lshl_add_u64 v[114:115], v[114:115], 0, v[132:133]
	v_mul_f32_e32 v107, v107, v107
	v_mul_f32_e32 v108, v108, v108
	v_cvt_pk_bf16_f32 v106, v110, v106
	v_cvt_pk_bf16_f32 v107, v107, v108
	v_cvt_pk_bf16_f32 v108, v116, v111
	v_cvt_pk_bf16_f32 v109, v112, v109
	global_store_dwordx4 v[114:115], v[106:109], off nt
	v_pk_mul_f32 v[56:57], v[56:57], v[142:143] op_sel_hi:[1,0]
	v_mul_f32_e32 v70, v70, v70
	v_mul_f32_e32 v106, v98, v98
	v_max_f32_e32 v98, 0, v103
	v_mul_f32_e32 v103, v99, v99
	v_max_f32_e32 v99, 0, v104
	v_mul_f32_e32 v104, v100, v100
	v_max_f32_e32 v100, 0, v105
	v_mul_f32_e32 v98, v98, v98
	v_mul_f32_e32 v99, v99, v99
	v_mul_f32_e32 v100, v100, v100
	v_cvt_pk_bf16_f32 v98, v102, v98
	v_cvt_pk_bf16_f32 v99, v99, v100
	v_cvt_pk_bf16_f32 v100, v106, v103
	v_cvt_pk_bf16_f32 v101, v104, v101
	global_store_dwordx4 v[114:115], v[98:101], off offset:256 nt
	v_mul_f32_e32 v69, v69, v69
	v_pk_mul_f32 v[60:61], v[60:61], v[142:143] op_sel_hi:[1,0]
	v_lshlrev_b64 v[98:99], 13, v[170:171]
	v_mul_f32_e32 v100, v90, v90
	v_max_f32_e32 v90, 0, v95
	v_lshl_add_u64 v[98:99], s[0:1], 0, v[98:99]
	v_mul_f32_e32 v90, v90, v90
	v_mul_f32_e32 v95, v91, v91
	v_max_f32_e32 v91, 0, v96
	v_mul_f32_e32 v96, v92, v92
	v_max_f32_e32 v92, 0, v97
	v_lshl_add_u64 v[98:99], v[98:99], 0, v[132:133]
	v_mul_f32_e32 v91, v91, v91
	v_mul_f32_e32 v92, v92, v92
	v_cvt_pk_bf16_f32 v90, v94, v90
	v_cvt_pk_bf16_f32 v91, v91, v92
	v_cvt_pk_bf16_f32 v92, v100, v95
	v_cvt_pk_bf16_f32 v93, v96, v93
	global_store_dwordx4 v[98:99], v[90:93], off nt
	v_pk_mul_f32 v[58:59], v[58:59], v[142:143] op_sel_hi:[1,0]
	v_max_f32_e32 v56, 0, v56
	v_mul_f32_e32 v90, v82, v82
	v_max_f32_e32 v82, 0, v87
	v_mul_f32_e32 v87, v83, v83
	v_max_f32_e32 v83, 0, v88
	v_mul_f32_e32 v88, v84, v84
	v_max_f32_e32 v84, 0, v89
	v_mul_f32_e32 v82, v82, v82
	v_mul_f32_e32 v83, v83, v83
	v_mul_f32_e32 v84, v84, v84
	v_cvt_pk_bf16_f32 v82, v86, v82
	v_cvt_pk_bf16_f32 v83, v83, v84
	v_cvt_pk_bf16_f32 v84, v90, v87
	v_cvt_pk_bf16_f32 v85, v88, v85
	global_store_dwordx4 v[98:99], v[82:85], off offset:256 nt
	v_pk_mul_f32 v[62:63], v[62:63], v[142:143] op_sel_hi:[1,0]
	v_max_f32_e32 v57, 0, v57
	v_lshlrev_b64 v[82:83], 13, v[168:169]
	v_mul_f32_e32 v84, v74, v74
	v_max_f32_e32 v74, 0, v79
	v_lshl_add_u64 v[82:83], s[0:1], 0, v[82:83]
	v_mul_f32_e32 v74, v74, v74
	v_mul_f32_e32 v79, v75, v75
	v_max_f32_e32 v75, 0, v80
	v_mul_f32_e32 v80, v76, v76
	v_max_f32_e32 v76, 0, v81
	v_lshl_add_u64 v[82:83], v[82:83], 0, v[132:133]
	v_mul_f32_e32 v75, v75, v75
	v_mul_f32_e32 v76, v76, v76
	v_cvt_pk_bf16_f32 v74, v78, v74
	v_cvt_pk_bf16_f32 v75, v75, v76
	v_cvt_pk_bf16_f32 v76, v84, v79
	v_cvt_pk_bf16_f32 v77, v80, v77
	global_store_dwordx4 v[82:83], v[74:77], off nt
	v_max_f32_e32 v58, 0, v58
	v_max_f32_e32 v60, 0, v60
	v_mul_f32_e32 v74, v66, v66
	v_max_f32_e32 v66, 0, v71
	v_mul_f32_e32 v71, v67, v67
	v_max_f32_e32 v67, 0, v72
	v_mul_f32_e32 v72, v68, v68
	v_max_f32_e32 v68, 0, v73
	v_mul_f32_e32 v66, v66, v66
	v_mul_f32_e32 v67, v67, v67
	v_mul_f32_e32 v68, v68, v68
	v_cvt_pk_bf16_f32 v66, v70, v66
	v_cvt_pk_bf16_f32 v67, v67, v68
	v_cvt_pk_bf16_f32 v68, v74, v71
	v_cvt_pk_bf16_f32 v69, v72, v69
	global_store_dwordx4 v[82:83], v[66:69], off offset:256 nt
	v_max_f32_e32 v59, 0, v59
	v_pk_mul_f32 v[50:51], v[50:51], v[142:143] op_sel_hi:[1,0]
	v_lshlrev_b64 v[66:67], 13, v[166:167]
	v_mul_f32_e32 v68, v56, v56
	v_max_f32_e32 v56, 0, v61
	v_lshl_add_u64 v[66:67], s[0:1], 0, v[66:67]
	v_mul_f32_e32 v56, v56, v56
	v_mul_f32_e32 v61, v57, v57
	v_max_f32_e32 v57, 0, v62
	v_mul_f32_e32 v62, v58, v58
	v_max_f32_e32 v58, 0, v63
	v_pk_mul_f32 v[48:49], v[48:49], v[142:143] op_sel_hi:[1,0]
	v_lshl_add_u64 v[66:67], v[66:67], 0, v[132:133]
	v_mul_f32_e32 v60, v60, v60
	v_mul_f32_e32 v57, v57, v57
	v_mul_f32_e32 v58, v58, v58
	v_mul_f32_e32 v59, v59, v59
	v_cvt_pk_bf16_f32 v56, v60, v56
	v_pk_mul_f32 v[54:55], v[54:55], v[142:143] op_sel_hi:[1,0]
	v_pk_mul_f32 v[52:53], v[52:53], v[142:143] op_sel_hi:[1,0]
	v_max_f32_e32 v48, 0, v48
	v_max_f32_e32 v49, 0, v49
	v_max_f32_e32 v50, 0, v50
	v_cvt_pk_bf16_f32 v57, v57, v58
	v_cvt_pk_bf16_f32 v58, v68, v61
	v_cvt_pk_bf16_f32 v59, v62, v59
	global_store_dwordx4 v[66:67], v[56:59], off nt
	v_max_f32_e32 v52, 0, v52
	v_max_f32_e32 v51, 0, v51
	v_mul_f32_e32 v56, v48, v48
	v_max_f32_e32 v48, 0, v53
	v_mul_f32_e32 v53, v49, v49
	v_max_f32_e32 v49, 0, v54
	v_mul_f32_e32 v54, v50, v50
	v_max_f32_e32 v50, 0, v55
	v_mul_f32_e32 v48, v48, v48
	v_mul_f32_e32 v49, v49, v49
	v_mul_f32_e32 v50, v50, v50
	v_pk_mul_f32 v[40:41], v[40:41], v[138:139] op_sel_hi:[1,0]
	v_mul_f32_e32 v52, v52, v52
	v_mul_f32_e32 v51, v51, v51
	v_cvt_pk_bf16_f32 v48, v52, v48
	v_cvt_pk_bf16_f32 v49, v49, v50
	v_cvt_pk_bf16_f32 v50, v56, v53
	v_pk_mul_f32 v[44:45], v[44:45], v[138:139] op_sel_hi:[1,0]
	v_pk_mul_f32 v[42:43], v[42:43], v[138:139] op_sel_hi:[1,0]
	v_max_f32_e32 v40, 0, v40
	v_cvt_pk_bf16_f32 v51, v54, v51
	global_store_dwordx4 v[66:67], v[48:51], off offset:256 nt
	v_pk_mul_f32 v[46:47], v[46:47], v[138:139] op_sel_hi:[1,0]
	v_max_f32_e32 v41, 0, v41
	v_lshlrev_b64 v[48:49], 13, v[164:165]
	v_mul_f32_e32 v50, v40, v40
	v_max_f32_e32 v40, 0, v45
	v_max_f32_e32 v42, 0, v42
	v_lshl_add_u64 v[48:49], s[0:1], 0, v[48:49]
	v_max_f32_e32 v44, 0, v44
	v_mul_f32_e32 v40, v40, v40
	v_mul_f32_e32 v45, v41, v41
	v_max_f32_e32 v41, 0, v46
	v_mul_f32_e32 v46, v42, v42
	v_max_f32_e32 v42, 0, v47
	v_max_f32_e32 v43, 0, v43
	v_pk_mul_f32 v[34:35], v[34:35], v[138:139] op_sel_hi:[1,0]
	v_pk_mul_f32 v[32:33], v[32:33], v[138:139] op_sel_hi:[1,0]
	v_lshl_add_u64 v[48:49], v[48:49], 0, v[132:133]
	v_mul_f32_e32 v44, v44, v44
	v_mul_f32_e32 v41, v41, v41
	v_mul_f32_e32 v42, v42, v42
	v_mul_f32_e32 v43, v43, v43
	v_cvt_pk_bf16_f32 v40, v44, v40
	v_pk_mul_f32 v[38:39], v[38:39], v[138:139] op_sel_hi:[1,0]
	v_pk_mul_f32 v[36:37], v[36:37], v[138:139] op_sel_hi:[1,0]
	v_max_f32_e32 v32, 0, v32
	v_max_f32_e32 v33, 0, v33
	v_max_f32_e32 v34, 0, v34
	v_cvt_pk_bf16_f32 v41, v41, v42
	v_cvt_pk_bf16_f32 v42, v50, v45
	v_cvt_pk_bf16_f32 v43, v46, v43
	global_store_dwordx4 v[48:49], v[40:43], off nt
	v_max_f32_e32 v36, 0, v36
	v_max_f32_e32 v35, 0, v35
	v_mul_f32_e32 v40, v32, v32
	v_max_f32_e32 v32, 0, v37
	v_mul_f32_e32 v37, v33, v33
	v_max_f32_e32 v33, 0, v38
	v_mul_f32_e32 v38, v34, v34
	v_max_f32_e32 v34, 0, v39
	v_mul_f32_e32 v32, v32, v32
	v_mul_f32_e32 v33, v33, v33
	v_mul_f32_e32 v34, v34, v34
	v_pk_mul_f32 v[24:25], v[24:25], v[134:135] op_sel_hi:[1,0]
	v_mul_f32_e32 v36, v36, v36
	v_mul_f32_e32 v35, v35, v35
	v_cvt_pk_bf16_f32 v32, v36, v32
	v_cvt_pk_bf16_f32 v33, v33, v34
	v_cvt_pk_bf16_f32 v34, v40, v37
	v_pk_mul_f32 v[28:29], v[28:29], v[134:135] op_sel_hi:[1,0]
	v_pk_mul_f32 v[26:27], v[26:27], v[134:135] op_sel_hi:[1,0]
	v_max_f32_e32 v24, 0, v24
	v_cvt_pk_bf16_f32 v35, v38, v35
	global_store_dwordx4 v[48:49], v[32:35], off offset:256 nt
	v_pk_mul_f32 v[30:31], v[30:31], v[134:135] op_sel_hi:[1,0]
	v_max_f32_e32 v25, 0, v25
	v_lshlrev_b64 v[32:33], 13, v[162:163]
	v_mul_f32_e32 v34, v24, v24
	v_max_f32_e32 v24, 0, v29
	v_max_f32_e32 v26, 0, v26
	v_lshl_add_u64 v[32:33], s[0:1], 0, v[32:33]
	v_max_f32_e32 v28, 0, v28
	v_mul_f32_e32 v24, v24, v24
	v_mul_f32_e32 v29, v25, v25
	v_max_f32_e32 v25, 0, v30
	v_mul_f32_e32 v30, v26, v26
	v_max_f32_e32 v26, 0, v31
	v_max_f32_e32 v27, 0, v27
	v_pk_mul_f32 v[18:19], v[18:19], v[134:135] op_sel_hi:[1,0]
	v_pk_mul_f32 v[16:17], v[16:17], v[134:135] op_sel_hi:[1,0]
	v_lshl_add_u64 v[32:33], v[32:33], 0, v[132:133]
	v_mul_f32_e32 v28, v28, v28
	v_mul_f32_e32 v25, v25, v25
	v_mul_f32_e32 v26, v26, v26
	v_mul_f32_e32 v27, v27, v27
	v_cvt_pk_bf16_f32 v24, v28, v24
	v_pk_mul_f32 v[22:23], v[22:23], v[134:135] op_sel_hi:[1,0]
	v_pk_mul_f32 v[20:21], v[20:21], v[134:135] op_sel_hi:[1,0]
	v_max_f32_e32 v16, 0, v16
	v_max_f32_e32 v17, 0, v17
	v_max_f32_e32 v18, 0, v18
	v_cvt_pk_bf16_f32 v25, v25, v26
	v_cvt_pk_bf16_f32 v26, v34, v29
	v_cvt_pk_bf16_f32 v27, v30, v27
	global_store_dwordx4 v[32:33], v[24:27], off nt
	v_max_f32_e32 v20, 0, v20
	v_max_f32_e32 v19, 0, v19
	v_mul_f32_e32 v24, v16, v16
	v_max_f32_e32 v16, 0, v21
	v_mul_f32_e32 v21, v17, v17
	v_max_f32_e32 v17, 0, v22
	v_mul_f32_e32 v22, v18, v18
	v_max_f32_e32 v18, 0, v23
	v_mul_f32_e32 v16, v16, v16
	v_mul_f32_e32 v17, v17, v17
	v_mul_f32_e32 v18, v18, v18
	v_pk_mul_f32 v[8:9], v[8:9], v[130:131] op_sel_hi:[1,0]
	v_mul_f32_e32 v20, v20, v20
	v_mul_f32_e32 v19, v19, v19
	v_cvt_pk_bf16_f32 v16, v20, v16
	v_cvt_pk_bf16_f32 v17, v17, v18
	v_cvt_pk_bf16_f32 v18, v24, v21
	v_pk_mul_f32 v[12:13], v[12:13], v[130:131] op_sel_hi:[1,0]
	v_pk_mul_f32 v[10:11], v[10:11], v[130:131] op_sel_hi:[1,0]
	v_max_f32_e32 v8, 0, v8
	v_cvt_pk_bf16_f32 v19, v22, v19
	global_store_dwordx4 v[32:33], v[16:19], off offset:256 nt
	v_pk_mul_f32 v[14:15], v[14:15], v[130:131] op_sel_hi:[1,0]
	v_max_f32_e32 v9, 0, v9
	v_lshlrev_b64 v[16:17], 13, v[160:161]
	v_mul_f32_e32 v18, v8, v8
	v_max_f32_e32 v8, 0, v13
	v_max_f32_e32 v10, 0, v10
	v_lshl_add_u64 v[16:17], s[0:1], 0, v[16:17]
	v_max_f32_e32 v12, 0, v12
	v_mul_f32_e32 v8, v8, v8
	v_mul_f32_e32 v13, v9, v9
	v_max_f32_e32 v9, 0, v14
	v_mul_f32_e32 v14, v10, v10
	v_max_f32_e32 v10, 0, v15
	v_max_f32_e32 v11, 0, v11
	v_pk_mul_f32 v[2:3], v[2:3], v[130:131] op_sel_hi:[1,0]
	v_pk_mul_f32 v[0:1], v[0:1], v[130:131] op_sel_hi:[1,0]
	v_lshl_add_u64 v[16:17], v[16:17], 0, v[132:133]
	v_mul_f32_e32 v12, v12, v12
	v_mul_f32_e32 v9, v9, v9
	v_mul_f32_e32 v10, v10, v10
	v_mul_f32_e32 v11, v11, v11
	v_cvt_pk_bf16_f32 v8, v12, v8
	v_pk_mul_f32 v[6:7], v[6:7], v[130:131] op_sel_hi:[1,0]
	v_pk_mul_f32 v[4:5], v[4:5], v[130:131] op_sel_hi:[1,0]
	v_max_f32_e32 v0, 0, v0
	v_max_f32_e32 v1, 0, v1
	v_max_f32_e32 v2, 0, v2
	v_cvt_pk_bf16_f32 v9, v9, v10
	v_cvt_pk_bf16_f32 v10, v18, v13
	v_cvt_pk_bf16_f32 v11, v14, v11
	global_store_dwordx4 v[16:17], v[8:11], off nt
	v_max_f32_e32 v3, 0, v3
	v_max_f32_e32 v4, 0, v4
	v_mul_f32_e32 v8, v0, v0
	v_max_f32_e32 v0, 0, v5
	v_mul_f32_e32 v5, v1, v1
	v_max_f32_e32 v1, 0, v6
	v_mul_f32_e32 v6, v2, v2
	v_max_f32_e32 v2, 0, v7
	v_mul_f32_e32 v0, v0, v0
	v_mul_f32_e32 v1, v1, v1
	v_mul_f32_e32 v2, v2, v2
	v_mul_f32_e32 v3, v3, v3
	s_mov_b64 s[0:1], -1
	s_andn2_b64 vcc, exec, s[42:43]
	v_mul_f32_e32 v4, v4, v4
	v_cvt_pk_bf16_f32 v0, v4, v0
	v_cvt_pk_bf16_f32 v1, v1, v2
	v_cvt_pk_bf16_f32 v2, v8, v5
	v_cvt_pk_bf16_f32 v3, v6, v3
	global_store_dwordx4 v[16:17], v[0:3], off offset:256 nt
	s_branch .Lff1_join
